# RG-LRU: sqrt(1 - a*a) evaluated with one fma from a = exp(log_a) instead of the degree-7 series of -expm1(2 log_a), in both direction loops (f32, same formula as the reference)
# speedup vs baseline: 1.0125x; 1.0040x over previous
; #define LAS __attribute__((address_space(3)))
; __device__ __forceinline__ float bf2f(bf16_t b) { return __uint_as_float(((unsigned)b) << 16); }
; __device__ __forceinline__ float sigmoidf_(float x) { return __builtin_amdgcn_rcpf(1.0f + __expf(-x)); }
; __device__ __forceinline__ f32x4 mfma16(bf16x8 a, bf16x8 b, f32x4 c) { return __builtin_amdgcn_mfma_f32_16x16x32_bf16(a, b, c, 0, 0, 0); }
; template <int DIR> __device__ __forceinline__ void lru_dir(const Params& p, int l, int n, int h, int lane, LAS bf16_t* XC, LAS float* STA, LAS float* STU) {
;     ...
;         f32x4 za[4], zx[4];
; #pragma unroll
;         for (int nf = 0; nf < 4; ++nf) { za[nf] = (f32x4){0.f, 0.f, 0.f, 0.f}; zx[nf] = za[nf];
;             za[nf] = mfma16(wa[nf][0], xf[0], za[nf]); za[nf] = mfma16(wa[nf][1], xf[1], za[nf]);
;             zx[nf] = mfma16(wx[nf][0], xf[0], zx[nf]); zx[nf] = mfma16(wx[nf][1], xf[1], zx[nf]); }
; #pragma unroll
;         for (int nf = 0; nf < 4; ++nf) {
;             const int jo = 16 * nf + 4 * q;
;             const bf16x4 xc4 = *(const LAS bf16x4*)(XC + (16 * mi + c) * 520 + 64 * h + jo);
;             const f32x4 zav = za[nf] + ba4[nf], zxv = zx[nf] + bx4[nf];
;             f32x4 av, uv;
; #pragma unroll
;             for (int r = 0; r < 4; ++r) {
;                 const float ra = sigmoidf_(zav[r]), ix = sigmoidf_(zxv[r]);
;                 const float la = ra * sp4[nf][r];
;                 av[r] = __expf(la);
;                 const float x2 = 2.0f * la;
;                 const float om = -x2 * (1.0f + x2 * (0.5f + x2 * (0.16666667f + x2 * (0.041666668f + x2 * (0.0083333338f + x2 * (0.0013888889f + x2 * 0.0001984127f))))));
;                 uv[r] = bf2f((bf16_t)xc4[r]) * ix * __builtin_amdgcn_sqrtf(fmaxf(om, 0.f));
;             }
;             *(LAS f32x4*)(STA + c * 68 + jo) = av; *(LAS f32x4*)(STU + c * 68 + jo) = uv;
.Llru0_loop:
	ds_read_b128 v[172:175], v150
	ds_read_b128 v[178:181], v150 offset:64
	ds_read_b64 v[182:183], v151
	ds_read_b64 v[184:185], v151 offset:32
	ds_read_b64 v[186:187], v151 offset:64
	ds_read_b64 v[188:189], v151 offset:96
	s_add_u32 s64, s66, s0
	s_addc_u32 s65, s67, 0
	s_waitcnt lgkmcnt(4)
	v_mfma_f32_16x16x32_bf16 v[156:159], v[4:7], v[172:175], 0
	v_mfma_f32_16x16x32_bf16 v[96:99], v[0:3], v[172:175], 0
	v_mfma_f32_16x16x32_bf16 v[160:163], v[24:27], v[172:175], 0
	v_mfma_f32_16x16x32_bf16 v[100:103], v[32:35], v[172:175], 0
	v_mfma_f32_16x16x32_bf16 v[164:167], v[48:51], v[172:175], 0
	v_mfma_f32_16x16x32_bf16 v[104:107], v[56:59], v[172:175], 0
	v_mfma_f32_16x16x32_bf16 v[168:171], v[72:75], v[172:175], 0
	v_mfma_f32_16x16x32_bf16 v[108:111], v[80:83], v[172:175], 0
	v_mfma_f32_16x16x32_bf16 v[156:159], v[8:11], v[178:181], v[156:159]
	v_mfma_f32_16x16x32_bf16 v[96:99], v[12:15], v[178:181], v[96:99]
	v_mfma_f32_16x16x32_bf16 v[160:163], v[28:31], v[178:181], v[160:163]
	v_mfma_f32_16x16x32_bf16 v[100:103], v[36:39], v[178:181], v[100:103]
	v_mfma_f32_16x16x32_bf16 v[164:167], v[52:55], v[178:181], v[164:167]
	v_mfma_f32_16x16x32_bf16 v[104:107], v[60:63], v[178:181], v[104:107]
	v_mfma_f32_16x16x32_bf16 v[168:171], v[76:79], v[178:181], v[168:171]
	v_mfma_f32_16x16x32_bf16 v[108:111], v[84:87], v[178:181], v[108:111]
	s_waitcnt lgkmcnt(0)
	v_lshlrev_b32_e32 v204, 16, v182
	v_and_b32_e32 v205, 0xffff0000, v182
	v_lshlrev_b32_e32 v206, 16, v183
	v_and_b32_e32 v207, 0xffff0000, v183
	v_lshlrev_b32_e32 v208, 16, v184
	v_and_b32_e32 v209, 0xffff0000, v184
	v_lshlrev_b32_e32 v210, 16, v185
	v_and_b32_e32 v211, 0xffff0000, v185
	v_lshlrev_b32_e32 v212, 16, v186
	v_and_b32_e32 v213, 0xffff0000, v186
	v_lshlrev_b32_e32 v214, 16, v187
	v_and_b32_e32 v215, 0xffff0000, v187
	v_lshlrev_b32_e32 v216, 16, v188
	v_and_b32_e32 v217, 0xffff0000, v188
	v_lshlrev_b32_e32 v218, 16, v189
	v_and_b32_e32 v219, 0xffff0000, v189
	v_add_f32_e32 v192, v16, v156
	v_add_f32_e32 v195, v17, v157
	v_add_f32_e32 v198, v18, v158
	v_add_f32_e32 v201, v19, v159
	v_add_f32_e32 v193, v20, v96
	v_add_f32_e32 v196, v21, v97
	v_add_f32_e32 v199, v22, v98
	v_add_f32_e32 v202, v23, v99
	v_mul_f32_e32 v192, 0xbfb8aa3b, v192
	v_mul_f32_e32 v195, 0xbfb8aa3b, v195
	v_mul_f32_e32 v198, 0xbfb8aa3b, v198
	v_mul_f32_e32 v201, 0xbfb8aa3b, v201
	v_mul_f32_e32 v193, 0xbfb8aa3b, v193
	v_mul_f32_e32 v196, 0xbfb8aa3b, v196
	v_mul_f32_e32 v199, 0xbfb8aa3b, v199
	v_mul_f32_e32 v202, 0xbfb8aa3b, v202
	v_exp_f32_e32 v192, v192
	v_exp_f32_e32 v195, v195
	v_exp_f32_e32 v198, v198
	v_exp_f32_e32 v201, v201
	v_exp_f32_e32 v193, v193
	v_exp_f32_e32 v196, v196
	v_exp_f32_e32 v199, v199
	v_exp_f32_e32 v202, v202
	v_add_f32_e32 v192, 1.0, v192
	v_add_f32_e32 v195, 1.0, v195
	v_add_f32_e32 v198, 1.0, v198
	v_add_f32_e32 v201, 1.0, v201
	v_add_f32_e32 v193, 1.0, v193
	v_add_f32_e32 v196, 1.0, v196
	v_add_f32_e32 v199, 1.0, v199
	v_add_f32_e32 v202, 1.0, v202
	v_rcp_f32_e32 v192, v192
	v_rcp_f32_e32 v195, v195
	v_rcp_f32_e32 v198, v198
	v_rcp_f32_e32 v201, v201
	v_rcp_f32_e32 v193, v193
	v_rcp_f32_e32 v196, v196
	v_rcp_f32_e32 v199, v199
	v_rcp_f32_e32 v202, v202
	v_mul_f32_e32 v192, v148, v192
	v_mul_f32_e32 v195, v147, v195
	v_mul_f32_e32 v198, v146, v198
	v_mul_f32_e32 v201, v145, v201
	v_mul_f32_e32 v194, 0x3fb8aa3b, v192
	v_mul_f32_e32 v197, 0x3fb8aa3b, v195
	v_mul_f32_e32 v200, 0x3fb8aa3b, v198
	v_mul_f32_e32 v203, 0x3fb8aa3b, v201
	v_exp_f32_e32 v156, v194
	v_exp_f32_e32 v157, v197
	v_exp_f32_e32 v158, v200
	v_exp_f32_e32 v159, v203
	v_fma_f32 v192, -v156, v156, 1.0
	v_fma_f32 v195, -v157, v157, 1.0
	v_fma_f32 v198, -v158, v158, 1.0
	v_fma_f32 v201, -v159, v159, 1.0
	v_max_f32_e32 v192, 0, v192
	v_max_f32_e32 v195, 0, v195
	v_max_f32_e32 v198, 0, v198
	v_max_f32_e32 v201, 0, v201
	v_sqrt_f32_e32 v192, v192
	v_sqrt_f32_e32 v195, v195
	v_sqrt_f32_e32 v198, v198
	v_sqrt_f32_e32 v201, v201
	v_mul_f32_e32 v193, v193, v204
	v_mul_f32_e32 v196, v196, v205
	v_mul_f32_e32 v199, v199, v206
	v_mul_f32_e32 v202, v202, v207
	v_mul_f32_e32 v96, v193, v192
	v_mul_f32_e32 v97, v196, v195
	v_mul_f32_e32 v98, v199, v198
	v_mul_f32_e32 v99, v202, v201
	ds_write_b128 v154, v[156:159]
	ds_write_b128 v154, v[96:99] offset:4352
	v_add_f32_e32 v192, v40, v160
	v_add_f32_e32 v195, v41, v161
	v_add_f32_e32 v198, v42, v162
	v_add_f32_e32 v201, v43, v163
	v_add_f32_e32 v193, v44, v100
	v_add_f32_e32 v196, v45, v101
	v_add_f32_e32 v199, v46, v102
	v_add_f32_e32 v202, v47, v103
	v_mul_f32_e32 v192, 0xbfb8aa3b, v192
	v_mul_f32_e32 v195, 0xbfb8aa3b, v195
	v_mul_f32_e32 v198, 0xbfb8aa3b, v198
	v_mul_f32_e32 v201, 0xbfb8aa3b, v201
	v_mul_f32_e32 v193, 0xbfb8aa3b, v193
	v_mul_f32_e32 v196, 0xbfb8aa3b, v196
	v_mul_f32_e32 v199, 0xbfb8aa3b, v199
	v_mul_f32_e32 v202, 0xbfb8aa3b, v202
	v_exp_f32_e32 v192, v192
	v_exp_f32_e32 v195, v195
	v_exp_f32_e32 v198, v198
	v_exp_f32_e32 v201, v201
	v_exp_f32_e32 v193, v193
	v_exp_f32_e32 v196, v196
	v_exp_f32_e32 v199, v199
	v_exp_f32_e32 v202, v202
	v_add_f32_e32 v192, 1.0, v192
	v_add_f32_e32 v195, 1.0, v195
	v_add_f32_e32 v198, 1.0, v198
	v_add_f32_e32 v201, 1.0, v201
	v_add_f32_e32 v193, 1.0, v193
	v_add_f32_e32 v196, 1.0, v196
	v_add_f32_e32 v199, 1.0, v199
	v_add_f32_e32 v202, 1.0, v202
	v_rcp_f32_e32 v192, v192
	v_rcp_f32_e32 v195, v195
	v_rcp_f32_e32 v198, v198
	v_rcp_f32_e32 v201, v201
	v_rcp_f32_e32 v193, v193
	v_rcp_f32_e32 v196, v196
	v_rcp_f32_e32 v199, v199
	v_rcp_f32_e32 v202, v202
	v_mul_f32_e32 v192, v144, v192
	v_mul_f32_e32 v195, v143, v195
	v_mul_f32_e32 v198, v142, v198
	v_mul_f32_e32 v201, v141, v201
	v_mul_f32_e32 v194, 0x3fb8aa3b, v192
	v_mul_f32_e32 v197, 0x3fb8aa3b, v195
; #define LAS __attribute__((address_space(3)))
; __device__ __forceinline__ float bf2f(bf16_t b) { return __uint_as_float(((unsigned)b) << 16); }
; __device__ __forceinline__ float sigmoidf_(float x) { return __builtin_amdgcn_rcpf(1.0f + __expf(-x)); }
; template <int DIR> __device__ __forceinline__ void lru_dir(const Params& p, int l, int n, int h, int lane, LAS bf16_t* XC, LAS float* STA, LAS float* STU) {
;     ...
;         for (int nf = 0; nf < 4; ++nf) {
;             const int jo = 16 * nf + 4 * q;
;             const bf16x4 xc4 = *(const LAS bf16x4*)(XC + (16 * mi + c) * 520 + 64 * h + jo);
;             const f32x4 zav = za[nf] + ba4[nf], zxv = zx[nf] + bx4[nf];
;             f32x4 av, uv;
; #pragma unroll
;             for (int r = 0; r < 4; ++r) {
;                 const float ra = sigmoidf_(zav[r]), ix = sigmoidf_(zxv[r]);
;                 const float la = ra * sp4[nf][r];
;                 av[r] = __expf(la);
;                 const float x2 = 2.0f * la;
;                 const float om = -x2 * (1.0f + x2 * (0.5f + x2 * (0.16666667f + x2 * (0.041666668f + x2 * (0.0083333338f + x2 * (0.0013888889f + x2 * 0.0001984127f))))));
;                 uv[r] = bf2f((bf16_t)xc4[r]) * ix * __builtin_amdgcn_sqrtf(fmaxf(om, 0.f));
;             }
;             *(LAS f32x4*)(STA + c * 68 + jo) = av; *(LAS f32x4*)(STU + c * 68 + jo) = uv;
	v_mul_f32_e32 v200, 0x3fb8aa3b, v198
	v_mul_f32_e32 v203, 0x3fb8aa3b, v201
	v_exp_f32_e32 v160, v194
	v_exp_f32_e32 v161, v197
	v_exp_f32_e32 v162, v200
	v_exp_f32_e32 v163, v203
	v_fma_f32 v192, -v160, v160, 1.0
	v_fma_f32 v195, -v161, v161, 1.0
	v_fma_f32 v198, -v162, v162, 1.0
	v_fma_f32 v201, -v163, v163, 1.0
	v_max_f32_e32 v192, 0, v192
	v_max_f32_e32 v195, 0, v195
	v_max_f32_e32 v198, 0, v198
	v_max_f32_e32 v201, 0, v201
	v_sqrt_f32_e32 v192, v192
	v_sqrt_f32_e32 v195, v195
	v_sqrt_f32_e32 v198, v198
	v_sqrt_f32_e32 v201, v201
	v_mul_f32_e32 v193, v193, v208
	v_mul_f32_e32 v196, v196, v209
	v_mul_f32_e32 v199, v199, v210
	v_mul_f32_e32 v202, v202, v211
	v_mul_f32_e32 v100, v193, v192
	v_mul_f32_e32 v101, v196, v195
	v_mul_f32_e32 v102, v199, v198
	v_mul_f32_e32 v103, v202, v201
	ds_write_b128 v154, v[160:163] offset:64
	ds_write_b128 v154, v[100:103] offset:4416
	v_add_f32_e32 v192, v64, v164
	v_add_f32_e32 v195, v65, v165
	v_add_f32_e32 v198, v66, v166
	v_add_f32_e32 v201, v67, v167
	v_add_f32_e32 v193, v68, v104
	v_add_f32_e32 v196, v69, v105
	v_add_f32_e32 v199, v70, v106
	v_add_f32_e32 v202, v71, v107
	v_mul_f32_e32 v192, 0xbfb8aa3b, v192
	v_mul_f32_e32 v195, 0xbfb8aa3b, v195
	v_mul_f32_e32 v198, 0xbfb8aa3b, v198
	v_mul_f32_e32 v201, 0xbfb8aa3b, v201
	v_mul_f32_e32 v193, 0xbfb8aa3b, v193
	v_mul_f32_e32 v196, 0xbfb8aa3b, v196
	v_mul_f32_e32 v199, 0xbfb8aa3b, v199
	v_mul_f32_e32 v202, 0xbfb8aa3b, v202
	v_exp_f32_e32 v192, v192
	v_exp_f32_e32 v195, v195
	v_exp_f32_e32 v198, v198
	v_exp_f32_e32 v201, v201
	v_exp_f32_e32 v193, v193
	v_exp_f32_e32 v196, v196
	v_exp_f32_e32 v199, v199
	v_exp_f32_e32 v202, v202
	v_add_f32_e32 v192, 1.0, v192
	v_add_f32_e32 v195, 1.0, v195
	v_add_f32_e32 v198, 1.0, v198
	v_add_f32_e32 v201, 1.0, v201
	v_add_f32_e32 v193, 1.0, v193
	v_add_f32_e32 v196, 1.0, v196
	v_add_f32_e32 v199, 1.0, v199
	v_add_f32_e32 v202, 1.0, v202
	v_rcp_f32_e32 v192, v192
	v_rcp_f32_e32 v195, v195
	v_rcp_f32_e32 v198, v198
	v_rcp_f32_e32 v201, v201
	v_rcp_f32_e32 v193, v193
	v_rcp_f32_e32 v196, v196
	v_rcp_f32_e32 v199, v199
	v_rcp_f32_e32 v202, v202
	v_mul_f32_e32 v192, v140, v192
	v_mul_f32_e32 v195, v139, v195
	v_mul_f32_e32 v198, v138, v198
	v_mul_f32_e32 v201, v137, v201
	v_mul_f32_e32 v194, 0x3fb8aa3b, v192
	v_mul_f32_e32 v197, 0x3fb8aa3b, v195
	v_mul_f32_e32 v200, 0x3fb8aa3b, v198
	v_mul_f32_e32 v203, 0x3fb8aa3b, v201
	v_exp_f32_e32 v164, v194
	v_exp_f32_e32 v165, v197
	v_exp_f32_e32 v166, v200
	v_exp_f32_e32 v167, v203
	v_fma_f32 v192, -v164, v164, 1.0
	v_fma_f32 v195, -v165, v165, 1.0
	v_fma_f32 v198, -v166, v166, 1.0
	v_fma_f32 v201, -v167, v167, 1.0
	v_max_f32_e32 v192, 0, v192
	v_max_f32_e32 v195, 0, v195
	v_max_f32_e32 v198, 0, v198
	v_max_f32_e32 v201, 0, v201
	v_sqrt_f32_e32 v192, v192
	v_sqrt_f32_e32 v195, v195
	v_sqrt_f32_e32 v198, v198
	v_sqrt_f32_e32 v201, v201
	v_mul_f32_e32 v193, v193, v212
	v_mul_f32_e32 v196, v196, v213
	v_mul_f32_e32 v199, v199, v214
	v_mul_f32_e32 v202, v202, v215
	v_mul_f32_e32 v104, v193, v192
	v_mul_f32_e32 v105, v196, v195
	v_mul_f32_e32 v106, v199, v198
	v_mul_f32_e32 v107, v202, v201
	ds_write_b128 v154, v[164:167] offset:128
	ds_write_b128 v154, v[104:107] offset:4480
	v_add_f32_e32 v192, v88, v168
	v_add_f32_e32 v195, v89, v169
	v_add_f32_e32 v198, v90, v170
	v_add_f32_e32 v201, v91, v171
	v_add_f32_e32 v193, v92, v108
	v_add_f32_e32 v196, v93, v109
	v_add_f32_e32 v199, v94, v110
	v_add_f32_e32 v202, v95, v111
	v_mul_f32_e32 v192, 0xbfb8aa3b, v192
	v_mul_f32_e32 v195, 0xbfb8aa3b, v195
	v_mul_f32_e32 v198, 0xbfb8aa3b, v198
	v_mul_f32_e32 v201, 0xbfb8aa3b, v201
	v_mul_f32_e32 v193, 0xbfb8aa3b, v193
	v_mul_f32_e32 v196, 0xbfb8aa3b, v196
	v_mul_f32_e32 v199, 0xbfb8aa3b, v199
	v_mul_f32_e32 v202, 0xbfb8aa3b, v202
	v_exp_f32_e32 v192, v192
	v_exp_f32_e32 v195, v195
	v_exp_f32_e32 v198, v198
	v_exp_f32_e32 v201, v201
	v_exp_f32_e32 v193, v193
	v_exp_f32_e32 v196, v196
	v_exp_f32_e32 v199, v199
	v_exp_f32_e32 v202, v202
	v_add_f32_e32 v192, 1.0, v192
	v_add_f32_e32 v195, 1.0, v195
	v_add_f32_e32 v198, 1.0, v198
	v_add_f32_e32 v201, 1.0, v201
	v_add_f32_e32 v193, 1.0, v193
	v_add_f32_e32 v196, 1.0, v196
	v_add_f32_e32 v199, 1.0, v199
	v_add_f32_e32 v202, 1.0, v202
	v_rcp_f32_e32 v192, v192
	v_rcp_f32_e32 v195, v195
	v_rcp_f32_e32 v198, v198
	v_rcp_f32_e32 v201, v201
	v_rcp_f32_e32 v193, v193
	v_rcp_f32_e32 v196, v196
	v_rcp_f32_e32 v199, v199
	v_rcp_f32_e32 v202, v202
	v_mul_f32_e32 v192, v136, v192
	v_mul_f32_e32 v195, v135, v195
	v_mul_f32_e32 v198, v134, v198
	v_mul_f32_e32 v201, v149, v201
	v_mul_f32_e32 v194, 0x3fb8aa3b, v192
	v_mul_f32_e32 v197, 0x3fb8aa3b, v195
	v_mul_f32_e32 v200, 0x3fb8aa3b, v198
	v_mul_f32_e32 v203, 0x3fb8aa3b, v201
	v_exp_f32_e32 v168, v194
	v_exp_f32_e32 v169, v197
	v_exp_f32_e32 v170, v200
	v_exp_f32_e32 v171, v203
	v_fma_f32 v192, -v168, v168, 1.0
	v_fma_f32 v195, -v169, v169, 1.0
	v_fma_f32 v198, -v170, v170, 1.0
	v_fma_f32 v201, -v171, v171, 1.0
	v_max_f32_e32 v192, 0, v192
	v_max_f32_e32 v195, 0, v195
	v_max_f32_e32 v198, 0, v198
	v_max_f32_e32 v201, 0, v201
	v_sqrt_f32_e32 v192, v192
	v_sqrt_f32_e32 v195, v195
	v_sqrt_f32_e32 v198, v198
	v_sqrt_f32_e32 v201, v201
	v_mul_f32_e32 v193, v193, v216
	v_mul_f32_e32 v196, v196, v217
	v_mul_f32_e32 v199, v199, v218
	v_mul_f32_e32 v202, v202, v219
	v_mul_f32_e32 v108, v193, v192
	v_mul_f32_e32 v109, v196, v195
	v_mul_f32_e32 v110, v199, v198
	v_mul_f32_e32 v111, v202, v201
	ds_write_b128 v154, v[168:171] offset:192
	ds_write_b128 v154, v[108:111] offset:4544
	s_waitcnt lgkmcnt(0)
; __device__ __forceinline__ float bf2f(bf16_t b) { return __uint_as_float(((unsigned)b) << 16); }
; __device__ __forceinline__ unsigned cvtpk(float lo, float hi) { const f32x2 v = (f32x2){lo, hi}; const bf16v2 b = __builtin_convertvector(v, bf16v2); return __builtin_bit_cast(unsigned, b); }
; #define LDS_FENCE() asm volatile("s_waitcnt lgkmcnt(0)" ::: "memory")
; template <int DIR> __device__ __forceinline__ void lru_dir(const Params& p, int l, int n, int h, int lane, LAS bf16_t* XC, LAS float* STA, LAS float* STU) {
;     ...
;         float aa[16], uu[16];
; #pragma unroll
;         for (int s = 0; s < 16; ++s) { aa[s] = STA[s * 68 + j]; uu[s] = STU[s * 68 + j]; }
;         LDS_FENCE();
; #pragma unroll
;         for (int s = 0; s < 16; ++s) {
;             const int tl = DIR == 0 ? s : 15 - s;
;             hcar = aa[tl] * hcar + uu[tl]; P *= aa[tl];
;             const size_t row = (size_t)(t0 + 16 * mi + tl);
;             if (DIR == 0) { const unsigned w = cvtpk(hcar, P); y[row * D + 64 * h + j] = (bf16_t)(w & 0xffffu); y[row * D + 512 + 64 * h + j] = (bf16_t)(w >> 16); }
;             else { const unsigned w = cvtpk(bf2f(hfp[tl]) + hcar, P); y[row * D + 64 * h + j] = (bf16_t)(w & 0xffffu); __builtin_nontemporal_store((bf16_t)(w >> 16), PB + row * 512 + 64 * h + j); }
;         }
	ds_read_b32 v204, v155
	ds_read_b32 v172, v155 offset:4352
	ds_read_b32 v205, v155 offset:272
	ds_read_b32 v173, v155 offset:4624
	ds_read_b32 v206, v155 offset:544
	ds_read_b32 v174, v155 offset:4896
	ds_read_b32 v207, v155 offset:816
	ds_read_b32 v175, v155 offset:5168
	ds_read_b32 v208, v155 offset:1088
	ds_read_b32 v178, v155 offset:5440
	ds_read_b32 v209, v155 offset:1360
	ds_read_b32 v179, v155 offset:5712
	ds_read_b32 v210, v155 offset:1632
	ds_read_b32 v180, v155 offset:5984
	ds_read_b32 v211, v155 offset:1904
	ds_read_b32 v181, v155 offset:6256
	s_waitcnt lgkmcnt(14)
	v_fma_f32 v130, v130, v204, v172
	v_mul_f32_e32 v129, v129, v204
	v_cvt_pk_bf16_f32 v190, v130, v129
	global_store_short v220, v190, s[64:65] offset:-4096
	global_store_short_d16_hi v220, v190, s[64:65] offset:-3072
	ds_read_b32 v212, v155 offset:2176
	ds_read_b32 v182, v155 offset:6528
	s_waitcnt lgkmcnt(14)
	v_fma_f32 v130, v130, v205, v173
	v_mul_f32_e32 v129, v129, v205
	v_cvt_pk_bf16_f32 v191, v130, v129
	global_store_short v220, v191, s[64:65] offset:-2048
	global_store_short_d16_hi v220, v191, s[64:65] offset:-1024
	ds_read_b32 v213, v155 offset:2448
	ds_read_b32 v183, v155 offset:6800
	s_waitcnt lgkmcnt(14)
	v_fma_f32 v130, v130, v206, v174
	v_mul_f32_e32 v129, v129, v206
	v_cvt_pk_bf16_f32 v190, v130, v129
	global_store_short v220, v190, s[64:65] offset:0
	global_store_short_d16_hi v220, v190, s[64:65] offset:1024
	ds_read_b32 v214, v155 offset:2720
	ds_read_b32 v184, v155 offset:7072
	s_waitcnt lgkmcnt(14)
	v_fma_f32 v130, v130, v207, v175
	v_mul_f32_e32 v129, v129, v207
	v_cvt_pk_bf16_f32 v191, v130, v129
	global_store_short v220, v191, s[64:65] offset:2048
	global_store_short_d16_hi v220, v191, s[64:65] offset:3072
	ds_read_b32 v215, v155 offset:2992
	ds_read_b32 v185, v155 offset:7344
	s_waitcnt lgkmcnt(14)
	v_fma_f32 v130, v130, v208, v178
	v_mul_f32_e32 v129, v129, v208
	v_cvt_pk_bf16_f32 v190, v130, v129
	s_add_u32 s64, s64, 0x2000
	s_addc_u32 s65, s65, 0
	global_store_short v220, v190, s[64:65] offset:-4096
	global_store_short_d16_hi v220, v190, s[64:65] offset:-3072
	ds_read_b32 v216, v155 offset:3264
	ds_read_b32 v186, v155 offset:7616
	s_waitcnt lgkmcnt(14)
	v_fma_f32 v130, v130, v209, v179
	v_mul_f32_e32 v129, v129, v209
	v_cvt_pk_bf16_f32 v191, v130, v129
	global_store_short v220, v191, s[64:65] offset:-2048
	global_store_short_d16_hi v220, v191, s[64:65] offset:-1024
	ds_read_b32 v217, v155 offset:3536
	ds_read_b32 v187, v155 offset:7888
	s_waitcnt lgkmcnt(14)
	v_fma_f32 v130, v130, v210, v180
	v_mul_f32_e32 v129, v129, v210
	v_cvt_pk_bf16_f32 v190, v130, v129
	global_store_short v220, v190, s[64:65] offset:0
	global_store_short_d16_hi v220, v190, s[64:65] offset:1024
	ds_read_b32 v218, v155 offset:3808
	ds_read_b32 v188, v155 offset:8160
	s_waitcnt lgkmcnt(14)
	v_fma_f32 v130, v130, v211, v181
	v_mul_f32_e32 v129, v129, v211
	v_cvt_pk_bf16_f32 v191, v130, v129
	global_store_short v220, v191, s[64:65] offset:2048
	global_store_short_d16_hi v220, v191, s[64:65] offset:3072
	ds_read_b32 v219, v155 offset:4080
	ds_read_b32 v189, v155 offset:8432
	s_waitcnt lgkmcnt(14)
	v_fma_f32 v130, v130, v212, v182
	v_mul_f32_e32 v129, v129, v212
	v_cvt_pk_bf16_f32 v190, v130, v129
	s_add_u32 s64, s64, 0x2000
	s_addc_u32 s65, s65, 0
	global_store_short v220, v190, s[64:65] offset:-4096
	global_store_short_d16_hi v220, v190, s[64:65] offset:-3072
	s_waitcnt lgkmcnt(12)
	v_fma_f32 v130, v130, v213, v183
	v_mul_f32_e32 v129, v129, v213
	v_cvt_pk_bf16_f32 v191, v130, v129
	global_store_short v220, v191, s[64:65] offset:-2048
	global_store_short_d16_hi v220, v191, s[64:65] offset:-1024
	s_waitcnt lgkmcnt(10)
	v_fma_f32 v130, v130, v214, v184
	v_mul_f32_e32 v129, v129, v214
	v_cvt_pk_bf16_f32 v190, v130, v129
	global_store_short v220, v190, s[64:65] offset:0
	global_store_short_d16_hi v220, v190, s[64:65] offset:1024
	s_waitcnt lgkmcnt(8)
	v_fma_f32 v130, v130, v215, v185
	v_mul_f32_e32 v129, v129, v215
	v_cvt_pk_bf16_f32 v191, v130, v129
	global_store_short v220, v191, s[64:65] offset:2048
	global_store_short_d16_hi v220, v191, s[64:65] offset:3072
	s_waitcnt lgkmcnt(6)
	v_fma_f32 v130, v130, v216, v186
	v_mul_f32_e32 v129, v129, v216
	v_cvt_pk_bf16_f32 v190, v130, v129
	s_add_u32 s64, s64, 0x2000
	s_addc_u32 s65, s65, 0
	global_store_short v220, v190, s[64:65] offset:-4096
	global_store_short_d16_hi v220, v190, s[64:65] offset:-3072
	s_waitcnt lgkmcnt(4)
	v_fma_f32 v130, v130, v217, v187
	v_mul_f32_e32 v129, v129, v217
	v_cvt_pk_bf16_f32 v191, v130, v129
	global_store_short v220, v191, s[64:65] offset:-2048
	global_store_short_d16_hi v220, v191, s[64:65] offset:-1024
	s_waitcnt lgkmcnt(2)
	v_fma_f32 v130, v130, v218, v188
	v_mul_f32_e32 v129, v129, v218
	v_cvt_pk_bf16_f32 v190, v130, v129
	global_store_short v220, v190, s[64:65] offset:0
	global_store_short_d16_hi v220, v190, s[64:65] offset:1024
	s_waitcnt lgkmcnt(0)
	v_fma_f32 v130, v130, v219, v189
	v_mul_f32_e32 v129, v129, v219
	v_cvt_pk_bf16_f32 v191, v130, v129
	global_store_short v220, v191, s[64:65] offset:2048
	global_store_short_d16_hi v220, v191, s[64:65] offset:3072
	s_add_u32 s0, s0, 0x8000
	s_addc_u32 s1, s1, 0
	v_add_u32_e32 v150, 0x4100, v150
	v_add_u32_e32 v151, 0x4100, v151
	s_cmp_lg_u32 s0, 0x20000
	s_cbranch_scc1 .Llru0_loop
; template <int DIR> __device__ __forceinline__ void lru_dir(const Params& p, int l, int n, int h, int lane, LAS bf16_t* XC, LAS float* STA, LAS float* STU) {
;     ...
;     const float* lam = p.in[10] + (size_t)(l * 2 + DIR) * 512 + 64 * h; const float* b_a = p.in[7] + (size_t)(l * 2 + DIR) * 512 + 64 * h; const float* b_x = p.in[9] + (size_t)(l * 2 + DIR) * 512 + 64 * h;
;     const bf16_t* LWa = LW + ((size_t)(DIR * 2 + 0) * 8 + h) * 4096 + c * 64 + 8 * q; const bf16_t* LWx = LW + ((size_t)(DIR * 2 + 1) * 8 + h) * 4096 + c * 64 + 8 * q;
;     bf16x8 wa[4][2], wx[4][2]; f32x4 sp4[4], ba4[4], bx4[4];
; #pragma unroll
;     for (int nf = 0; nf < 4; ++nf) {
; #pragma unroll
;         for (int ks = 0; ks < 2; ++ks) { wa[nf][ks] = *(const bf16x8*)(LWa + nf * 1024 + 32 * ks); wx[nf][ks] = *(const bf16x8*)(LWx + nf * 1024 + 32 * ks); }
;         const f32x4 lam4 = *(const f32x4*)(lam + 16 * nf + 4 * q); ba4[nf] = *(const f32x4*)(b_a + 16 * nf + 4 * q); bx4[nf] = *(const f32x4*)(b_x + 16 * nf + 4 * q);
; #pragma unroll
;         for (int r = 0; r < 4; ++r) { const float e = __expf(-lam4[r]); const float l1p = e < 0.05f ? e * (1.0f - e * (0.5f - e * (0.33333334f - e * 0.25f))) : __logf(1.0f + e); sp4[nf][r] = -8.0f * l1p; }
;     }
;     ...
;     Aprod[(size_t)(DIR * NCH + n) * 512 + 64 * h + j] = P; Hend[(size_t)(DIR * NCH + n) * 512 + 64 * h + j] = hcar;
	v_add_u32_e32 v156, 0x1000, v155
	v_add_u32_e32 v157, 0x1200, v155
	v_add_u32_e32 v158, 0x400, v155
	v_add_u32_e32 v159, 0x1400, v155
	v_add_u32_e32 v160, 0x1600, v155
	v_add_u32_e32 v161, 0x800, v155
	v_add_u32_e32 v162, 0x1800, v155
	v_add_u32_e32 v163, 0x1a00, v155
	v_add_u32_e32 v164, 0xc00, v155
	v_add_u32_e32 v165, 0x1c00, v155
	v_add_u32_e32 v166, 0x1e00, v155
	s_ashr_i32 s5, s4, 31
	s_lshl_b64 s[0:1], s[4:5], 9
	v_lshl_add_u64 v[0:1], s[0:1], 0, v[124:125]
	v_or_b32_e32 v0, v0, v126
	v_readlane_b32 s0, v254, 11
	v_lshlrev_b64 v[0:1], 2, v[0:1]
	v_readlane_b32 s1, v254, 12
	v_lshlrev_b32_e32 v6, 1, v121
	v_mov_b32_e32 v7, v177
	v_lshl_add_u64 v[2:3], s[0:1], 0, v[0:1]
	v_readlane_b32 s0, v254, 13
	v_readlane_b32 s1, v254, 14
	v_lshlrev_b32_e32 v8, 1, v133
	v_mov_b32_e32 v9, v177
	v_lshl_add_u64 v[6:7], v[114:115], 0, v[6:7]
	v_lshl_add_u64 v[0:1], s[0:1], 0, v[0:1]
	v_lshl_add_u64 v[6:7], v[6:7], 0, v[8:9]
	s_mov_b64 s[0:1], 0x20000
	v_lshl_add_u64 v[80:81], v[6:7], 0, s[0:1]
	s_mov_b64 s[0:1], 0x30000
	global_store_dword v[0:1], v130, off
	v_lshl_add_u64 v[0:1], s[22:23], 0, v[112:113]
	v_lshl_add_u64 v[78:79], v[6:7], 0, s[0:1]
	v_mov_b32_e32 v121, v177
	s_mov_b32 s0, 0x20000
	v_lshl_add_u64 v[76:77], v[0:1], 0, v[120:121]
	v_add_co_u32_e32 v0, vcc, s0, v6
	v_lshl_add_u64 v[4:5], s[38:39], 0, v[112:113]
	s_nop 0
	v_addc_co_u32_e32 v1, vcc, 0, v7, vcc
	v_lshl_add_u64 v[92:93], v[4:5], 0, v[120:121]
	v_add_co_u32_e32 v4, vcc, 0x30000, v6
	global_store_dword v[2:3], v129, off
	v_lshl_add_u64 v[2:3], s[26:27], 0, v[112:113]
	v_addc_co_u32_e32 v5, vcc, 0, v7, vcc
	v_lshl_add_u64 v[88:89], v[2:3], 0, v[120:121]
	global_load_dwordx4 v[192:195], v[76:77], off
	global_load_dwordx4 v[196:199], v[76:77], off offset:64
	global_load_dwordx4 v[200:203], v[76:77], off offset:128
	global_load_dwordx4 v[204:207], v[76:77], off offset:192
	s_nop 0
	global_load_dwordx4 v[0:3], v[0:1], off
	s_nop 0
	global_load_dwordx4 v[4:7], v[4:5], off
	s_nop 0
	global_load_dwordx4 v[8:11], v[80:81], off offset:64
	global_load_dwordx4 v[12:15], v[78:79], off offset:64
	global_load_dwordx4 v[16:19], v[88:89], off
	global_load_dwordx4 v[20:23], v[92:93], off
	s_waitcnt vmcnt(6)
	v_mul_f32_e32 v24, 0xbfb8aa3b, v192
	v_exp_f32_e32 v24, v24
	s_nop 0
	v_cmp_ngt_f32_e32 vcc, s6, v24
	s_and_saveexec_b64 s[0:1], vcc
	s_xor_b64 s[30:31], exec, s[0:1]
	s_cbranch_execz .LBB0_260
	v_add_f32_e32 v24, 1.0, v24
	v_cmp_gt_f32_e32 vcc, s25, v24
	s_nop 1
	v_cndmask_b32_e64 v28, 0, 32, vcc
	v_ldexp_f32 v24, v24, v28
	v_log_f32_e32 v24, v24
	s_nop 0
	v_mul_f32_e32 v28, 0x3f317217, v24
	v_fma_f32 v28, v24, s36, -v28
	v_fmac_f32_e32 v28, 0x3377d1cf, v24
	v_fmac_f32_e32 v28, 0x3f317217, v24
	v_cmp_lt_f32_e64 s[0:1], |v24|, s37
	s_nop 1
	v_cndmask_b32_e64 v24, v24, v28, s[0:1]
	v_cndmask_b32_e32 v28, 0, v232, vcc
	v_sub_f32_e32 v100, v24, v28

; #define LAS __attribute__((address_space(3)))
; __device__ __forceinline__ float bf2f(bf16_t b) { return __uint_as_float(((unsigned)b) << 16); }
; __device__ __forceinline__ float sigmoidf_(float x) { return __builtin_amdgcn_rcpf(1.0f + __expf(-x)); }
; __device__ __forceinline__ f32x4 mfma16(bf16x8 a, bf16x8 b, f32x4 c) { return __builtin_amdgcn_mfma_f32_16x16x32_bf16(a, b, c, 0, 0, 0); }
; template <int DIR> __device__ __forceinline__ void lru_dir(const Params& p, int l, int n, int h, int lane, LAS bf16_t* XC, LAS float* STA, LAS float* STU) {
;     ...
;         bf16x8 xf[2];
; #pragma unroll
;         for (int ks = 0; ks < 2; ++ks) xf[ks] = *(const LAS bf16x8*)(XC + (16 * mi + c) * 520 + 64 * h + 32 * ks + 8 * q);
;         f32x4 za[4], zx[4];
; #pragma unroll
;         for (int nf = 0; nf < 4; ++nf) { za[nf] = (f32x4){0.f, 0.f, 0.f, 0.f}; zx[nf] = za[nf];
;             za[nf] = mfma16(wa[nf][0], xf[0], za[nf]); za[nf] = mfma16(wa[nf][1], xf[1], za[nf]);
;             zx[nf] = mfma16(wx[nf][0], xf[0], zx[nf]); zx[nf] = mfma16(wx[nf][1], xf[1], zx[nf]); }
; #pragma unroll
;         for (int nf = 0; nf < 4; ++nf) {
;             const int jo = 16 * nf + 4 * q;
;             const bf16x4 xc4 = *(const LAS bf16x4*)(XC + (16 * mi + c) * 520 + 64 * h + jo);
;             const f32x4 zav = za[nf] + ba4[nf], zxv = zx[nf] + bx4[nf];
;             f32x4 av, uv;
; #pragma unroll
;             for (int r = 0; r < 4; ++r) {
;                 const float ra = sigmoidf_(zav[r]), ix = sigmoidf_(zxv[r]);
;                 const float la = ra * sp4[nf][r];
;                 av[r] = __expf(la);
;                 const float x2 = 2.0f * la;
;                 const float om = -x2 * (1.0f + x2 * (0.5f + x2 * (0.16666667f + x2 * (0.041666668f + x2 * (0.0083333338f + x2 * (0.0013888889f + x2 * 0.0001984127f))))));
;                 uv[r] = bf2f((bf16_t)xc4[r]) * ix * __builtin_amdgcn_sqrtf(fmaxf(om, 0.f));
;             }
;             *(LAS f32x4*)(STA + c * 68 + jo) = av; *(LAS f32x4*)(STU + c * 68 + jo) = uv;
.LBB0_323:
	v_add_u32_e32 v133, s0, v127
	v_mad_u32_u24 v100, v133, s7, v188
	ds_read_b128 v[96:99], v100
	ds_read_b128 v[120:123], v100 offset:64
	v_mad_u32_u24 v133, v133, s7, v191
	ds_read_b64 v[146:147], v133
	v_lshl_add_u64 v[136:137], v[130:131], 0, v[176:177]
	s_waitcnt lgkmcnt(2)
	v_mfma_f32_16x16x32_bf16 v[100:103], v[0:3], v[96:99], 0
	s_mov_b32 s1, 0x1877000
	v_add_co_u32_e32 v150, vcc, s1, v136
	s_waitcnt lgkmcnt(1)
	v_mfma_f32_16x16x32_bf16 v[138:141], v[8:11], v[120:123], v[100:103]
	s_waitcnt lgkmcnt(0)
	v_and_b32_e32 v149, 0xffff0000, v147
	v_lshlrev_b32_e32 v148, 16, v147
	v_addc_co_u32_e32 v151, vcc, 0, v137, vcc
	v_mfma_f32_16x16x32_bf16 v[100:103], v[4:7], v[96:99], 0
	s_mov_b32 s1, 0x1876000
	v_and_b32_e32 v147, 0xffff0000, v146
	v_lshlrev_b32_e32 v146, 16, v146
	v_mfma_f32_16x16x32_bf16 v[142:145], v[12:15], v[120:123], v[100:103]
	global_load_ushort v189, v[150:151], off offset:2048
	global_load_ushort v204, v[150:151], off
	s_movk_i32 s28, 0xc000
	s_mov_b32 s29, -1
	v_mfma_f32_16x16x32_bf16 v[100:103], v[24:27], v[96:99], 0
	s_add_i32 s0, s0, -16
	s_cmp_lg_u32 s0, -16
	v_mfma_f32_16x16x32_bf16 v[116:119], v[28:31], v[120:123], v[100:103]
	v_mfma_f32_16x16x32_bf16 v[100:103], v[32:35], v[96:99], 0
	v_mfma_f32_16x16x32_bf16 v[112:115], v[36:39], v[120:123], v[100:103]
	s_nop 5
	v_add_f32_e32 v116, v40, v116
	v_mul_f32_e32 v116, 0xbfb8aa3b, v116
	v_exp_f32_e32 v116, v116
	v_mfma_f32_16x16x32_bf16 v[100:103], v[48:51], v[96:99], 0
	v_add_f32_e32 v117, v41, v117
	v_add_f32_e32 v112, v44, v112
	v_add_f32_e32 v116, 1.0, v116
	v_mfma_f32_16x16x32_bf16 v[108:111], v[52:55], v[120:123], v[100:103]
	v_mul_f32_e32 v112, 0xbfb8aa3b, v112
	v_exp_f32_e32 v112, v112
	v_mul_f32_e32 v117, 0xbfb8aa3b, v117
	v_mfma_f32_16x16x32_bf16 v[100:103], v[56:59], v[96:99], 0
	v_exp_f32_e32 v117, v117
	v_add_f32_e32 v112, 1.0, v112
	v_add_f32_e32 v113, v45, v113
	v_mfma_f32_16x16x32_bf16 v[104:107], v[60:63], v[120:123], v[100:103]
	v_add_f32_e32 v117, 1.0, v117
	v_mul_f32_e32 v113, 0xbfb8aa3b, v113
	v_exp_f32_e32 v113, v113
	s_waitcnt vmcnt(7)
	v_mfma_f32_16x16x32_bf16 v[100:103], v[72:75], v[96:99], 0
	v_add_f32_e32 v118, v42, v118
	v_mul_f32_e32 v118, 0xbfb8aa3b, v118
	v_add_f32_e32 v113, 1.0, v113
	s_waitcnt vmcnt(5)
	v_mfma_f32_16x16x32_bf16 v[96:99], v[80:83], v[96:99], 0
	v_exp_f32_e32 v118, v118
	v_add_f32_e32 v114, v46, v114
	v_mul_f32_e32 v114, 0xbfb8aa3b, v114
	v_mfma_f32_16x16x32_bf16 v[100:103], v[76:79], v[120:123], v[100:103]
	v_add_f32_e32 v118, 1.0, v118
	v_exp_f32_e32 v114, v114
	v_add_f32_e32 v119, v43, v119
	s_waitcnt vmcnt(4)
	v_mfma_f32_16x16x32_bf16 v[96:99], v[84:87], v[120:123], v[96:99]
	v_add_f32_e32 v120, v16, v138
	v_mul_f32_e32 v120, 0xbfb8aa3b, v120
	v_exp_f32_e32 v120, v120
	v_add_f32_e32 v121, v20, v142
	v_mul_f32_e32 v121, 0xbfb8aa3b, v121
	v_exp_f32_e32 v121, v121
	v_add_f32_e32 v120, 1.0, v120
	v_rcp_f32_e32 v120, v120
	v_add_f32_e32 v114, 1.0, v114
	v_add_f32_e32 v121, 1.0, v121
	v_rcp_f32_e32 v138, v121
	v_mul_f32_e32 v121, v187, v120
	v_mul_f32_e32 v120, 0x3fb8aa3b, v121
	v_exp_f32_e32 v120, v120
	s_nop 0
	v_fma_f32 v121, -v120, v120, 1.0
	v_max_f32_e32 v121, 0, v121
	v_sqrt_f32_e32 v142, v121
	v_add_f32_e32 v121, v17, v139
	v_mul_f32_e32 v121, 0xbfb8aa3b, v121
	v_exp_f32_e32 v121, v121
	v_add_f32_e32 v122, v21, v143
	v_mul_f32_e32 v122, 0xbfb8aa3b, v122
	v_exp_f32_e32 v122, v122
	v_add_f32_e32 v121, 1.0, v121
	v_rcp_f32_e32 v121, v121
	v_add_f32_e32 v122, 1.0, v122
	v_rcp_f32_e32 v139, v122
	v_mul_f32_e32 v122, v186, v121
	v_mul_f32_e32 v121, 0x3fb8aa3b, v122
	v_exp_f32_e32 v121, v121
	s_nop 0
	v_fma_f32 v122, -v121, v121, 1.0
	v_max_f32_e32 v122, 0, v122
	v_sqrt_f32_e32 v143, v122
	v_add_f32_e32 v122, v18, v140
	v_mul_f32_e32 v122, 0xbfb8aa3b, v122
	v_exp_f32_e32 v122, v122
	v_add_f32_e32 v123, v22, v144
	v_mul_f32_e32 v123, 0xbfb8aa3b, v123
	v_exp_f32_e32 v123, v123
	v_add_f32_e32 v122, 1.0, v122
	v_rcp_f32_e32 v122, v122
	v_pk_mul_f32 v[138:139], v[138:139], v[146:147]
	v_add_f32_e32 v123, 1.0, v123
	v_rcp_f32_e32 v140, v123
	v_mul_f32_e32 v123, v185, v122
	v_mul_f32_e32 v122, 0x3fb8aa3b, v123
	v_exp_f32_e32 v122, v122
	s_nop 0
	v_fma_f32 v123, -v122, v122, 1.0
	v_max_f32_e32 v123, 0, v123
	v_sqrt_f32_e32 v144, v123
	v_add_f32_e32 v123, v19, v141
	v_mul_f32_e32 v123, 0xbfb8aa3b, v123
	v_exp_f32_e32 v123, v123
	v_add_f32_e32 v134, v23, v145
	v_mul_f32_e32 v134, 0xbfb8aa3b, v134
	v_exp_f32_e32 v134, v134
	v_add_f32_e32 v123, 1.0, v123
	v_rcp_f32_e32 v123, v123
	v_pk_mul_f32 v[206:207], v[138:139], v[142:143]
	v_add_f32_e32 v134, 1.0, v134
	v_rcp_f32_e32 v141, v134
	v_mul_f32_e32 v134, v184, v123
	v_mul_f32_e32 v123, 0x3fb8aa3b, v134
	v_exp_f32_e32 v123, v123
	s_nop 0
	v_fma_f32 v134, -v123, v123, 1.0
	v_max_f32_e32 v134, 0, v134
	v_sqrt_f32_e32 v145, v134
	v_pk_mul_f32 v[140:141], v[140:141], v[148:149]
	v_add_co_u32_e32 v148, vcc, s1, v136
	s_mov_b32 s1, 0x1875000
	s_nop 0
	v_addc_co_u32_e32 v149, vcc, 0, v137, vcc
	v_add_co_u32_e32 v146, vcc, s1, v136
	s_mov_b32 s1, 0x1874000
	s_nop 0
	v_addc_co_u32_e32 v147, vcc, 0, v137, vcc
	v_pk_mul_f32 v[208:209], v[140:141], v[144:145]
	v_add_co_u32_e32 v144, vcc, s1, v136
	s_mov_b32 s1, 0x1873000
	s_nop 0
	v_addc_co_u32_e32 v145, vcc, 0, v137, vcc
	v_add_co_u32_e32 v142, vcc, s1, v136
	s_mov_b32 s1, 0x1872000
	s_nop 0
	v_addc_co_u32_e32 v143, vcc, 0, v137, vcc
	v_add_co_u32_e32 v140, vcc, s1, v136
	s_mov_b32 s1, 0x1871000
	s_nop 0
	v_addc_co_u32_e32 v141, vcc, 0, v137, vcc
	v_add_co_u32_e32 v138, vcc, s1, v136
	s_mov_b32 s1, 0x1870000
	s_nop 0
	v_addc_co_u32_e32 v139, vcc, 0, v137, vcc
	v_add_co_u32_e32 v136, vcc, s1, v136
	global_load_ushort v205, v[148:149], off offset:2048
; #define LAS __attribute__((address_space(3)))
; __device__ __forceinline__ float bf2f(bf16_t b) { return __uint_as_float(((unsigned)b) << 16); }
; __device__ __forceinline__ float sigmoidf_(float x) { return __builtin_amdgcn_rcpf(1.0f + __expf(-x)); }
; template <int DIR> __device__ __forceinline__ void lru_dir(const Params& p, int l, int n, int h, int lane, LAS bf16_t* XC, LAS float* STA, LAS float* STU) {
;     ...
;         for (int nf = 0; nf < 4; ++nf) {
;             const int jo = 16 * nf + 4 * q;
;             const bf16x4 xc4 = *(const LAS bf16x4*)(XC + (16 * mi + c) * 520 + 64 * h + jo);
;             const f32x4 zav = za[nf] + ba4[nf], zxv = zx[nf] + bx4[nf];
;             f32x4 av, uv;
; #pragma unroll
;             for (int r = 0; r < 4; ++r) {
;                 const float ra = sigmoidf_(zav[r]), ix = sigmoidf_(zxv[r]);
;                 const float la = ra * sp4[nf][r];
;                 av[r] = __expf(la);
;                 const float x2 = 2.0f * la;
;                 const float om = -x2 * (1.0f + x2 * (0.5f + x2 * (0.16666667f + x2 * (0.041666668f + x2 * (0.0083333338f + x2 * (0.0013888889f + x2 * 0.0001984127f))))));
;                 uv[r] = bf2f((bf16_t)xc4[r]) * ix * __builtin_amdgcn_sqrtf(fmaxf(om, 0.f));
;             }
;             *(LAS f32x4*)(STA + c * 68 + jo) = av; *(LAS f32x4*)(STU + c * 68 + jo) = uv;
	global_load_ushort v201, v[148:149], off
	v_addc_co_u32_e32 v137, vcc, 0, v137, vcc
	global_load_ushort v203, v[146:147], off offset:2048
	global_load_ushort v202, v[146:147], off
	global_load_ushort v193, v[144:145], off offset:2048
	global_load_ushort v134, v[144:145], off
	global_load_ushort v195, v[142:143], off offset:2048
	global_load_ushort v194, v[142:143], off
	global_load_ushort v197, v[140:141], off offset:2048
	global_load_ushort v196, v[140:141], off
	global_load_ushort v198, v[138:139], off offset:2048
	global_load_ushort v199, v[138:139], off
	global_load_ushort v200, v[136:137], off offset:2048
	global_load_ushort v192, v[136:137], off
	ds_write_b128 v154, v[120:123]
	ds_write_b128 v154, v[206:209] offset:4352
	v_rcp_f32_e32 v122, v116
	v_rcp_f32_e32 v116, v112
	v_mul_f32_e32 v119, 0xbfb8aa3b, v119
	v_exp_f32_e32 v119, v119
	v_mul_f32_e32 v122, v183, v122
	v_mul_f32_e32 v112, 0x3fb8aa3b, v122
	v_exp_f32_e32 v112, v112
	s_nop 0
	v_fma_f32 v122, -v112, v112, 1.0
	v_rcp_f32_e32 v123, v117
	v_rcp_f32_e32 v117, v113
	v_add_f32_e32 v115, v47, v115
	v_add_f32_e32 v119, 1.0, v119
	v_mul_f32_e32 v123, v182, v123
	v_mul_f32_e32 v113, 0x3fb8aa3b, v123
	v_exp_f32_e32 v113, v113
	s_nop 0
	v_fma_f32 v123, -v113, v113, 1.0
	v_rcp_f32_e32 v152, v118
	v_rcp_f32_e32 v118, v114
	v_mul_f32_e32 v115, 0xbfb8aa3b, v115
	v_exp_f32_e32 v115, v115
	v_mul_f32_e32 v152, v175, v152
	v_mul_f32_e32 v114, 0x3fb8aa3b, v152
	v_exp_f32_e32 v114, v114
	s_nop 0
	v_fma_f32 v152, -v114, v114, 1.0
	v_rcp_f32_e32 v153, v119
	v_add_f32_e32 v115, 1.0, v115
	v_rcp_f32_e32 v119, v115
	ds_read_b64 v[120:121], v133 offset:32
	v_mul_f32_e32 v153, v174, v153
	v_mul_f32_e32 v115, 0x3fb8aa3b, v153
	v_exp_f32_e32 v115, v115
	v_add_f32_e32 v108, v64, v108
	v_fma_f32 v153, -v115, v115, 1.0
	v_mul_f32_e32 v108, 0xbfb8aa3b, v108
	v_max_f32_e32 v122, 0, v122
	v_max_f32_e32 v123, 0, v123
	v_max_f32_e32 v152, 0, v152
	v_max_f32_e32 v153, 0, v153
	v_exp_f32_e32 v108, v108
	v_sqrt_f32_e32 v122, v122
	v_sqrt_f32_e32 v123, v123
	v_sqrt_f32_e32 v152, v152
	v_sqrt_f32_e32 v153, v153
	s_waitcnt lgkmcnt(0)
	v_and_b32_e32 v179, 0xffff0000, v120
	v_lshlrev_b32_e32 v178, 16, v120
	v_and_b32_e32 v181, 0xffff0000, v121
	v_lshlrev_b32_e32 v180, 16, v121
	v_add_f32_e32 v104, v68, v104
	v_pk_mul_f32 v[118:119], v[118:119], v[180:181]
	v_pk_mul_f32 v[116:117], v[116:117], v[178:179]
	v_add_f32_e32 v108, 1.0, v108
	v_mul_f32_e32 v104, 0xbfb8aa3b, v104
	v_pk_mul_f32 v[116:117], v[116:117], v[122:123]
	v_pk_mul_f32 v[118:119], v[118:119], v[152:153]
	ds_write_b128 v154, v[112:115] offset:64
	ds_write_b128 v154, v[116:119] offset:4416
	v_rcp_f32_e32 v114, v108
	v_exp_f32_e32 v104, v104
	v_add_f32_e32 v109, v65, v109
	v_mul_f32_e32 v109, 0xbfb8aa3b, v109
	v_mul_f32_e32 v114, v173, v114
	v_add_f32_e32 v104, 1.0, v104
	v_rcp_f32_e32 v108, v104
	v_mul_f32_e32 v104, 0x3fb8aa3b, v114
	v_exp_f32_e32 v104, v104
	v_exp_f32_e32 v109, v109
	v_add_f32_e32 v105, v69, v105
	v_add_f32_e32 v109, 1.0, v109
	v_mul_f32_e32 v105, 0xbfb8aa3b, v105
	v_fma_f32 v114, -v104, v104, 1.0
	v_rcp_f32_e32 v115, v109
	v_exp_f32_e32 v105, v105
	v_add_f32_e32 v110, v66, v110
	v_mul_f32_e32 v110, 0xbfb8aa3b, v110
	v_mul_f32_e32 v115, v172, v115
	v_add_f32_e32 v105, 1.0, v105
	v_rcp_f32_e32 v109, v105
	v_mul_f32_e32 v105, 0x3fb8aa3b, v115
	v_exp_f32_e32 v105, v105
	v_exp_f32_e32 v110, v110
	v_add_f32_e32 v106, v70, v106
	v_add_f32_e32 v110, 1.0, v110
	v_mul_f32_e32 v106, 0xbfb8aa3b, v106
	v_fma_f32 v115, -v105, v105, 1.0
	v_rcp_f32_e32 v116, v110
	v_exp_f32_e32 v106, v106
	v_add_f32_e32 v111, v67, v111
	v_mul_f32_e32 v111, 0xbfb8aa3b, v111
	v_mul_f32_e32 v116, v171, v116
	v_add_f32_e32 v106, 1.0, v106
	v_rcp_f32_e32 v110, v106
	v_mul_f32_e32 v106, 0x3fb8aa3b, v116
	v_exp_f32_e32 v106, v106
	v_exp_f32_e32 v111, v111
	v_add_f32_e32 v107, v71, v107
	v_add_f32_e32 v111, 1.0, v111
	v_mul_f32_e32 v107, 0xbfb8aa3b, v107
	v_fma_f32 v116, -v106, v106, 1.0
	v_rcp_f32_e32 v117, v111
	v_exp_f32_e32 v107, v107
	ds_read_b64 v[112:113], v133 offset:64
	s_waitcnt vmcnt(17)
	v_add_f32_e32 v100, v88, v100
	v_mul_f32_e32 v117, v170, v117
	v_add_f32_e32 v107, 1.0, v107
	v_rcp_f32_e32 v111, v107
	v_mul_f32_e32 v107, 0x3fb8aa3b, v117
	v_exp_f32_e32 v107, v107
	s_nop 0
	v_fma_f32 v117, -v107, v107, 1.0
	v_mul_f32_e32 v100, 0xbfb8aa3b, v100
	v_max_f32_e32 v114, 0, v114
	v_max_f32_e32 v115, 0, v115
	v_max_f32_e32 v116, 0, v116
	v_max_f32_e32 v117, 0, v117
	v_exp_f32_e32 v100, v100
	v_sqrt_f32_e32 v114, v114
	v_sqrt_f32_e32 v115, v115
	v_sqrt_f32_e32 v116, v116
	v_sqrt_f32_e32 v117, v117
	s_waitcnt lgkmcnt(0)
	v_and_b32_e32 v119, 0xffff0000, v112
	v_lshlrev_b32_e32 v118, 16, v112
	v_and_b32_e32 v121, 0xffff0000, v113
	v_lshlrev_b32_e32 v120, 16, v113
	s_waitcnt vmcnt(16)
; #define LAS __attribute__((address_space(3)))
; __device__ __forceinline__ float bf2f(bf16_t b) { return __uint_as_float(((unsigned)b) << 16); }
; __device__ __forceinline__ unsigned cvtpk(float lo, float hi) { const f32x2 v = (f32x2){lo, hi}; const bf16v2 b = __builtin_convertvector(v, bf16v2); return __builtin_bit_cast(unsigned, b); }
; __device__ __forceinline__ float sigmoidf_(float x) { return __builtin_amdgcn_rcpf(1.0f + __expf(-x)); }
; template <int DIR> __device__ __forceinline__ void lru_dir(const Params& p, int l, int n, int h, int lane, LAS bf16_t* XC, LAS float* STA, LAS float* STU) {
;     ...
;         for (int nf = 0; nf < 4; ++nf) {
;             const int jo = 16 * nf + 4 * q;
;             const bf16x4 xc4 = *(const LAS bf16x4*)(XC + (16 * mi + c) * 520 + 64 * h + jo);
;             const f32x4 zav = za[nf] + ba4[nf], zxv = zx[nf] + bx4[nf];
;             f32x4 av, uv;
; #pragma unroll
;             for (int r = 0; r < 4; ++r) {
;                 const float ra = sigmoidf_(zav[r]), ix = sigmoidf_(zxv[r]);
;                 const float la = ra * sp4[nf][r];
;                 av[r] = __expf(la);
;                 const float x2 = 2.0f * la;
;                 const float om = -x2 * (1.0f + x2 * (0.5f + x2 * (0.16666667f + x2 * (0.041666668f + x2 * (0.0083333338f + x2 * (0.0013888889f + x2 * 0.0001984127f))))));
;                 uv[r] = bf2f((bf16_t)xc4[r]) * ix * __builtin_amdgcn_sqrtf(fmaxf(om, 0.f));
;             }
;             *(LAS f32x4*)(STA + c * 68 + jo) = av; *(LAS f32x4*)(STU + c * 68 + jo) = uv;
;         }
;         LDS_FENCE();
;         float aa[16], uu[16];
; #pragma unroll
;         for (int s = 0; s < 16; ++s) { aa[s] = STA[s * 68 + j]; uu[s] = STU[s * 68 + j]; }
;         LDS_FENCE();
; #pragma unroll
;         for (int s = 0; s < 16; ++s) {
;             const int tl = DIR == 0 ? s : 15 - s;
;             hcar = aa[tl] * hcar + uu[tl]; P *= aa[tl];
;             const size_t row = (size_t)(t0 + 16 * mi + tl);
;             if (DIR == 0) { const unsigned w = cvtpk(hcar, P); y[row * D + 64 * h + j] = (bf16_t)(w & 0xffffu); y[row * D + 512 + 64 * h + j] = (bf16_t)(w >> 16); }
;             else { const unsigned w = cvtpk(bf2f(hfp[tl]) + hcar, P); y[row * D + 64 * h + j] = (bf16_t)(w & 0xffffu); __builtin_nontemporal_store((bf16_t)(w >> 16), PB + row * 512 + 64 * h + j); }
	v_add_f32_e32 v96, v92, v96
	v_pk_mul_f32 v[110:111], v[110:111], v[120:121]
	v_pk_mul_f32 v[108:109], v[108:109], v[118:119]
	v_add_f32_e32 v100, 1.0, v100
	v_mul_f32_e32 v96, 0xbfb8aa3b, v96
	v_pk_mul_f32 v[108:109], v[108:109], v[114:115]
	v_pk_mul_f32 v[110:111], v[110:111], v[116:117]
	ds_write_b128 v154, v[104:107] offset:128
	ds_write_b128 v154, v[108:111] offset:4480
	v_rcp_f32_e32 v106, v100
	v_exp_f32_e32 v96, v96
	v_add_f32_e32 v101, v89, v101
	v_mul_f32_e32 v101, 0xbfb8aa3b, v101
	v_mul_f32_e32 v106, v169, v106
	v_add_f32_e32 v96, 1.0, v96
	v_rcp_f32_e32 v100, v96
	v_mul_f32_e32 v96, 0x3fb8aa3b, v106
	v_exp_f32_e32 v96, v96
	v_exp_f32_e32 v101, v101
	v_add_f32_e32 v97, v93, v97
	v_add_f32_e32 v101, 1.0, v101
	v_mul_f32_e32 v97, 0xbfb8aa3b, v97
	v_fma_f32 v106, -v96, v96, 1.0
	v_rcp_f32_e32 v107, v101
	v_exp_f32_e32 v97, v97
	v_add_f32_e32 v102, v90, v102
	v_mul_f32_e32 v102, 0xbfb8aa3b, v102
	v_mul_f32_e32 v107, v168, v107
	v_add_f32_e32 v97, 1.0, v97
	v_rcp_f32_e32 v101, v97
	v_mul_f32_e32 v97, 0x3fb8aa3b, v107
	v_exp_f32_e32 v97, v97
	v_exp_f32_e32 v102, v102
	v_add_f32_e32 v98, v94, v98
	v_add_f32_e32 v102, 1.0, v102
	v_mul_f32_e32 v98, 0xbfb8aa3b, v98
	v_fma_f32 v107, -v97, v97, 1.0
	v_rcp_f32_e32 v108, v102
	v_exp_f32_e32 v98, v98
	v_add_f32_e32 v103, v91, v103
	v_mul_f32_e32 v103, 0xbfb8aa3b, v103
	v_mul_f32_e32 v108, v167, v108
	v_add_f32_e32 v98, 1.0, v98
	v_rcp_f32_e32 v102, v98
	v_mul_f32_e32 v98, 0x3fb8aa3b, v108
	v_exp_f32_e32 v98, v98
	v_exp_f32_e32 v103, v103
	v_add_f32_e32 v99, v95, v99
	v_add_f32_e32 v103, 1.0, v103
	v_mul_f32_e32 v99, 0xbfb8aa3b, v99
	v_fma_f32 v108, -v98, v98, 1.0
	v_rcp_f32_e32 v109, v103
	v_exp_f32_e32 v99, v99
	ds_read_b64 v[104:105], v133 offset:96
	v_max_f32_e32 v106, 0, v106
	v_mul_f32_e32 v109, v190, v109
	v_add_f32_e32 v99, 1.0, v99
	v_rcp_f32_e32 v103, v99
	v_mul_f32_e32 v99, 0x3fb8aa3b, v109
	v_exp_f32_e32 v99, v99
	s_nop 0
	v_fma_f32 v109, -v99, v99, 1.0
	v_max_f32_e32 v107, 0, v107
	v_max_f32_e32 v108, 0, v108
	v_max_f32_e32 v109, 0, v109
	v_sqrt_f32_e32 v106, v106
	v_sqrt_f32_e32 v107, v107
	v_sqrt_f32_e32 v108, v108
	v_sqrt_f32_e32 v109, v109
	s_waitcnt lgkmcnt(0)
	v_and_b32_e32 v111, 0xffff0000, v104
	v_lshlrev_b32_e32 v110, 16, v104
	v_and_b32_e32 v113, 0xffff0000, v105
	v_lshlrev_b32_e32 v112, 16, v105
	v_pk_mul_f32 v[102:103], v[102:103], v[112:113]
	v_pk_mul_f32 v[100:101], v[100:101], v[110:111]
	v_pk_mul_f32 v[102:103], v[102:103], v[108:109]
	v_pk_mul_f32 v[100:101], v[100:101], v[106:107]
	ds_write_b128 v154, v[96:99] offset:192
	ds_write_b128 v154, v[100:103] offset:4544
	s_waitcnt lgkmcnt(0)
	ds_read2_b32 v[152:153], v164 offset0:184 offset1:252
	ds_read2_b32 v[122:123], v166 offset0:120 offset1:188
	s_waitcnt vmcnt(14)
	v_lshlrev_b32_e32 v180, 16, v204
	s_mov_b32 s1, 0xd3e7000
	s_waitcnt lgkmcnt(1)
	v_mov_b32_e32 v211, v152
	s_waitcnt lgkmcnt(0)
	v_fma_f32 v178, v132, v153, v123
	ds_read2_b32 v[98:99], v155 offset1:68
	ds_read2_b32 v[96:97], v156 offset0:64 offset1:132
	ds_read2_b32 v[100:101], v155 offset0:136 offset1:204
	ds_read2_b32 v[102:103], v157 offset0:72 offset1:140
	ds_read2_b32 v[104:105], v158 offset0:16 offset1:84
	ds_read2_b32 v[108:109], v159 offset0:80 offset1:148
	ds_read2_b32 v[106:107], v158 offset0:152 offset1:220
	ds_read2_b32 v[112:113], v160 offset0:88 offset1:156
	ds_read2_b32 v[110:111], v161 offset0:32 offset1:100
	ds_read2_b32 v[114:115], v162 offset0:96 offset1:164
	ds_read2_b32 v[116:117], v161 offset0:168 offset1:236
	ds_read2_b32 v[118:119], v163 offset0:104 offset1:172
	ds_read2_b32 v[120:121], v164 offset0:48 offset1:116
	ds_read2_b32 v[132:133], v165 offset0:112 offset1:180
	v_fmac_f32_e32 v122, v152, v178
	v_mov_b32_e32 v123, v135
	v_lshlrev_b32_e32 v135, 16, v189
	v_add_f32_e32 v181, v122, v180
	s_waitcnt vmcnt(13)
	v_lshlrev_b32_e32 v180, 16, v205
	s_waitcnt lgkmcnt(1)
	v_mov_b32_e32 v204, v121
	v_mov_b32_e32 v205, v153
	v_add_f32_e32 v135, v178, v135
	v_lshl_add_u64 v[178:179], v[128:129], 0, v[176:177]
	v_pk_mul_f32 v[206:207], v[204:205], v[122:123]
	s_waitcnt lgkmcnt(0)
	v_mov_b32_e32 v210, v133
	v_add_co_u32_e32 v208, vcc, s1, v178
	v_pk_mul_f32 v[152:153], v[210:211], v[206:207]
	v_cvt_pk_bf16_f32 v135, v135, v207
	v_addc_co_u32_e32 v209, vcc, 0, v179, vcc
	v_pk_fma_f32 v[122:123], v[204:205], v[122:123], v[210:211]
	v_cvt_pk_bf16_f32 v133, v181, v153
	v_mov_b32_e32 v181, v121
	s_waitcnt lgkmcnt(0)
	global_store_short v[150:151], v135, off offset:2048
	global_store_short_d16_hi v[208:209], v135, off offset:3072 nt
	global_store_short v[150:151], v133, off
	global_store_short_d16_hi v[208:209], v133, off offset:2048 nt
	v_pk_add_f32 v[150:151], v[122:123], v[180:181]
	v_pk_mul_f32 v[152:153], v[152:153], v[180:181]
	v_fmac_f32_e32 v132, v120, v122
	v_cvt_pk_bf16_f32 v121, v150, v153
	global_store_short v[148:149], v121, off offset:2048
	global_store_short_d16_hi v[208:209], v121, off offset:1024 nt
	s_waitcnt vmcnt(18)
	v_lshlrev_b32_e32 v121, 16, v201
	v_fmac_f32_e32 v119, v117, v132
	v_add_f32_e32 v123, v132, v121
	s_waitcnt vmcnt(17)
	v_lshlrev_b32_e32 v121, 16, v203
	v_mov_b32_e32 v132, v116
	v_mov_b32_e32 v133, v120
	v_mov_b32_e32 v152, v119
	v_add_f32_e32 v135, v119, v121
	v_pk_mul_f32 v[120:121], v[132:133], v[152:153]
	s_mov_b32 s1, 0xd3e6000
	v_cvt_pk_bf16_f32 v119, v123, v121
	global_store_short v[148:149], v119, off
	global_store_short_d16_hi v[208:209], v119, off nt
	v_mov_b32_e32 v119, v117
	v_pk_fma_f32 v[132:133], v[132:133], v[152:153], v[118:119]
	v_pk_mul_f32 v[118:119], v[118:119], v[120:121]
	v_add_co_u32_e32 v120, vcc, s1, v178
	s_waitcnt vmcnt(18)
; __device__ __forceinline__ float bf2f(bf16_t b) { return __uint_as_float(((unsigned)b) << 16); }
; __device__ __forceinline__ unsigned cvtpk(float lo, float hi) { const f32x2 v = (f32x2){lo, hi}; const bf16v2 b = __builtin_convertvector(v, bf16v2); return __builtin_bit_cast(unsigned, b); }
; template <int DIR> __device__ __forceinline__ void lru_dir(const Params& p, int l, int n, int h, int lane, LAS bf16_t* XC, LAS float* STA, LAS float* STU) {
;     ...
; #pragma unroll
;         for (int s = 0; s < 16; ++s) {
;             const int tl = DIR == 0 ? s : 15 - s;
;             hcar = aa[tl] * hcar + uu[tl]; P *= aa[tl];
;             const size_t row = (size_t)(t0 + 16 * mi + tl);
;             if (DIR == 0) { const unsigned w = cvtpk(hcar, P); y[row * D + 64 * h + j] = (bf16_t)(w & 0xffffu); y[row * D + 512 + 64 * h + j] = (bf16_t)(w >> 16); }
;             else { const unsigned w = cvtpk(bf2f(hfp[tl]) + hcar, P); y[row * D + 64 * h + j] = (bf16_t)(w & 0xffffu); __builtin_nontemporal_store((bf16_t)(w >> 16), PB + row * 512 + 64 * h + j); }
;         }
;     }
;     Aprod[(size_t)(DIR * NCH + n) * 512 + 64 * h + j] = P; Hend[(size_t)(DIR * NCH + n) * 512 + 64 * h + j] = hcar;
	v_lshlrev_b32_e32 v122, 16, v202
	v_mov_b32_e32 v118, v132
	v_cvt_pk_bf16_f32 v117, v135, v119
	v_addc_co_u32_e32 v121, vcc, 0, v179, vcc
	v_mov_b32_e32 v123, v116
	global_store_short v[146:147], v117, off offset:2048
	global_store_short_d16_hi v[120:121], v117, off offset:3072 nt
	v_pk_add_f32 v[116:117], v[132:133], v[122:123]
	v_pk_mul_f32 v[118:119], v[118:119], v[122:123]
	v_fma_f32 v115, v111, v132, v115
	v_cvt_pk_bf16_f32 v116, v116, v119
	global_store_short v[146:147], v116, off
	global_store_short_d16_hi v[120:121], v116, off offset:2048 nt
	s_waitcnt vmcnt(21)
	v_lshlrev_b32_e32 v116, 16, v193
	v_add_f32_e32 v116, v115, v116
	v_fmac_f32_e32 v114, v110, v115
	s_waitcnt vmcnt(20)
	v_lshlrev_b32_e32 v115, 16, v134
	v_add_f32_e32 v117, v114, v115
	v_fma_f32 v113, v107, v114, v113
	s_waitcnt vmcnt(19)
	v_lshlrev_b32_e32 v114, 16, v195
	v_add_f32_e32 v122, v113, v114
	v_fmac_f32_e32 v112, v106, v113
	s_waitcnt vmcnt(18)
	v_lshlrev_b32_e32 v113, 16, v194
	v_add_f32_e32 v123, v112, v113
	v_fmac_f32_e32 v109, v105, v112
	s_waitcnt vmcnt(17)
	v_lshlrev_b32_e32 v112, 16, v197
	v_add_f32_e32 v132, v109, v112
	v_mov_b32_e32 v112, v104
	v_mov_b32_e32 v113, v111
	v_mov_b32_e32 v118, v109
	v_pk_mul_f32 v[114:115], v[112:113], v[118:119]
	s_mov_b32 s1, 0xd3e5000
	v_cvt_pk_bf16_f32 v109, v116, v115
	global_store_short v[144:145], v109, off offset:2048
	global_store_short_d16_hi v[120:121], v109, off offset:1024 nt
	v_mov_b32_e32 v109, v110
	v_pk_fma_f32 v[110:111], v[112:113], v[118:119], v[108:109]
	v_pk_mul_f32 v[108:109], v[108:109], v[114:115]
	v_add_co_u32_e32 v114, vcc, s1, v178
	v_cvt_pk_bf16_f32 v108, v117, v109
	v_mov_b32_e32 v111, v109
	global_store_short v[144:145], v108, off
	global_store_short_d16_hi v[120:121], v108, off nt
	v_mov_b32_e32 v108, v101
	v_mov_b32_e32 v109, v107
	v_pk_mul_f32 v[112:113], v[108:109], v[110:111]
	v_addc_co_u32_e32 v115, vcc, 0, v179, vcc
	v_cvt_pk_bf16_f32 v107, v122, v113
	v_mov_b32_e32 v116, v103
	v_mov_b32_e32 v117, v106
	global_store_short v[142:143], v107, off offset:2048
	global_store_short_d16_hi v[114:115], v107, off offset:3072 nt
	v_pk_fma_f32 v[106:107], v[108:109], v[110:111], v[116:117]
	v_pk_mul_f32 v[108:109], v[116:117], v[112:113]
	s_waitcnt vmcnt(22)
	v_lshlrev_b32_e32 v133, 16, v196
	v_mov_b32_e32 v107, v109
	v_cvt_pk_bf16_f32 v103, v123, v109
	v_mov_b32_e32 v108, v100
	v_mov_b32_e32 v109, v105
	v_pk_mul_f32 v[112:113], v[108:109], v[106:107]
	global_store_short v[142:143], v103, off
	global_store_short_d16_hi v[114:115], v103, off offset:2048 nt
	v_cvt_pk_bf16_f32 v103, v132, v113
	global_store_short v[140:141], v103, off offset:2048
	global_store_short_d16_hi v[114:115], v103, off offset:1024 nt
	v_mov_b32_e32 v103, v104
	v_add_f32_e32 v110, v110, v133
	v_pk_fma_f32 v[104:105], v[108:109], v[106:107], v[102:103]
	v_pk_mul_f32 v[102:103], v[102:103], v[112:113]
	s_waitcnt vmcnt(25)
	v_lshlrev_b32_e32 v134, 16, v198
	v_cvt_pk_bf16_f32 v102, v110, v103
	v_mov_b32_e32 v105, v103
	global_store_short v[140:141], v102, off
	global_store_short_d16_hi v[114:115], v102, off nt
	v_mov_b32_e32 v102, v99
	v_mov_b32_e32 v103, v101
	v_add_f32_e32 v108, v106, v134
	v_pk_mul_f32 v[106:107], v[102:103], v[104:105]
	s_mov_b32 s1, 0xd3e4000
	v_cvt_pk_bf16_f32 v101, v108, v107
	v_add_co_u32_e32 v108, vcc, s1, v178
	s_waitcnt vmcnt(26)
	v_lshlrev_b32_e32 v135, 16, v199
	v_addc_co_u32_e32 v109, vcc, 0, v179, vcc
	v_mov_b32_e32 v110, v97
	v_mov_b32_e32 v111, v100
	global_store_short v[138:139], v101, off offset:2048
	global_store_short_d16_hi v[108:109], v101, off offset:3072 nt
	v_add_f32_e32 v112, v104, v135
	v_pk_fma_f32 v[100:101], v[102:103], v[104:105], v[110:111]
	v_pk_mul_f32 v[102:103], v[110:111], v[106:107]
	s_waitcnt vmcnt(27)
	v_lshlrev_b32_e32 v146, 16, v200
	v_mov_b32_e32 v101, v103
	v_cvt_pk_bf16_f32 v97, v112, v103
	global_store_short v[138:139], v97, off
	global_store_short_d16_hi v[108:109], v97, off offset:2048 nt
	v_add_f32_e32 v97, v100, v146
	v_pk_mul_f32 v[102:103], v[98:99], v[100:101]
	v_lshl_add_u64 v[128:129], v[128:129], 0, s[28:29]
	v_cvt_pk_bf16_f32 v97, v97, v103
	global_store_short v[136:137], v97, off offset:2048
	global_store_short_d16_hi v[108:109], v97, off offset:1024 nt
	v_mov_b32_e32 v97, v98
	v_pk_fma_f32 v[132:133], v[98:99], v[100:101], v[96:97]
	v_pk_mul_f32 v[134:135], v[96:97], v[102:103]
	s_waitcnt vmcnt(30)
	v_lshlrev_b32_e32 v96, 16, v192
	s_movk_i32 s28, 0x8000
	v_add_f32_e32 v96, v132, v96
	s_mov_b32 s29, -1
	v_cvt_pk_bf16_f32 v96, v96, v135
	v_lshl_add_u64 v[130:131], v[130:131], 0, s[28:29]
	global_store_short v[136:137], v96, off
	global_store_short_d16_hi v[108:109], v96, off nt
	s_cbranch_scc1 .LBB0_323
	s_lshl_b64 s[0:1], s[4:5], 9
	s_add_u32 s0, s0, 0x20000
	s_addc_u32 s1, s1, 0
	v_lshl_add_u64 v[0:1], s[0:1], 0, v[124:125]
	v_or_b32_e32 v0, v0, v126
	v_readlane_b32 s0, v254, 11
	v_lshlrev_b64 v[0:1], 2, v[0:1]
	v_readlane_b32 s1, v254, 12
	s_nop 1
	v_lshl_add_u64 v[2:3], s[0:1], 0, v[0:1]
	v_readlane_b32 s0, v254, 13
	v_readlane_b32 s1, v254, 14
	global_store_dword v[2:3], v135, off
	s_nop 0
	v_lshl_add_u64 v[0:1], s[0:1], 0, v[0:1]
	v_readlane_b32 s0, v255, 8
	v_readlane_b32 s1, v255, 9
	global_store_dword v[0:1], v132, off
	s_barrier
	s_load_dword s0, s[0:1], 0x0
	s_waitcnt lgkmcnt(0)
	s_add_i32 s4, s0, s4
	s_cmpk_gt_i32 s4, 0xff
	s_cbranch_scc0 .LBB0_192
